# P9 conv epilogue: packed f32 ops split into scalar mul/fmac/add pairs (bit-identical; packed VOP3P f32 issues slower than two scalar ops)
# speedup vs baseline: 1.0086x; 1.0086x over previous
; __device__ __forceinline__ float dpp_ror1(float v) { return __int_as_float(__builtin_amdgcn_update_dpp(0, __float_as_int(v), 0x121, 0xf, 0xf, false)); }
; __device__ __forceinline__ float dpp_rol1(float v) { return __int_as_float(__builtin_amdgcn_update_dpp(0, __float_as_int(v), 0x12F, 0xf, 0xf, false)); }
;     __device__ __forceinline__ void tile(const f32x4 (&acc)[2][2][4][2], const Unit& u, int wr, int wc, int fr, int fq) const {
;     ...
;                         const float xv = acc[ai][0][m][n][i], xg = acc[ai][1][m][n][i];
;                         const float uv = m > 0 ? acc[ai][0][m > 0 ? m - 1 : 0][n][i] : 0.f, ug = m > 0 ? acc[ai][1][m > 0 ? m - 1 : 0][n][i] : 0.f;
;                         const float dv = m < 3 ? acc[ai][0][m < 3 ? m + 1 : 3][n][i] : 0.f, dg = m < 3 ? acc[ai][1][m < 3 ? m + 1 : 3][n][i] : 0.f;
;                         const float pv = dpp_ror1(fr == 15 ? uv : xv), pg = dpp_ror1(fr == 15 ? ug : xg);
;                         const float nv = dpp_rol1(fr == 0 ? dv : xv), ng = dpp_rol1(fr == 0 ? dg : xg);
;                         const float yv = wv0[i] * pv + wv1[i] * xv + wv2[i] * nv + bv[i];
;                         const float yg = wg0[i] * pg + wg1[i] * xg + wg2[i] * ng + bg[i];
.Lp9c_nowait:
	v_mov_b32_dpp v216, v96 row_shr:1 row_mask:0xf bank_mask:0xf bound_ctrl:1
	v_mov_b32_dpp v217, v97 row_shr:1 row_mask:0xf bank_mask:0xf bound_ctrl:1
	v_mov_b32_dpp v218, v98 row_shr:1 row_mask:0xf bank_mask:0xf bound_ctrl:1
	v_mov_b32_dpp v219, v99 row_shr:1 row_mask:0xf bank_mask:0xf bound_ctrl:1
	v_mov_b32_dpp v220, v152 row_shl:1 row_mask:0xf bank_mask:0xf bound_ctrl:1
	v_mov_b32_dpp v221, v153 row_shl:1 row_mask:0xf bank_mask:0xf bound_ctrl:1
	v_mov_b32_dpp v222, v154 row_shl:1 row_mask:0xf bank_mask:0xf bound_ctrl:1
	v_mov_b32_dpp v223, v155 row_shl:1 row_mask:0xf bank_mask:0xf bound_ctrl:1
	v_mul_f32_e32 v176, v152, v234
	v_mul_f32_e32 v177, v153, v235
	v_mul_f32_e32 v178, v154, v236
	v_mul_f32_e32 v179, v155, v237
	v_mul_f32_e32 v180, v112, v234
	v_mul_f32_e32 v181, v113, v235
	v_mul_f32_e32 v182, v114, v236
	v_mul_f32_e32 v183, v115, v237
	v_mul_f32_e32 v184, v104, v234
	v_mul_f32_e32 v185, v105, v235
	v_mul_f32_e32 v186, v106, v236
	v_mul_f32_e32 v187, v107, v237
	v_mul_f32_e32 v224, v96, v234
	v_mul_f32_e32 v225, v97, v235
	v_mul_f32_e32 v226, v98, v236
	v_mul_f32_e32 v227, v99, v237
	v_fmac_f32_e32 v176, v230, v216
	v_fmac_f32_e32 v177, v231, v217
	v_fmac_f32_e32 v178, v232, v218
	v_fmac_f32_e32 v179, v233, v219
	v_fmac_f32_e32 v180, v230, v152
	v_fmac_f32_e32 v181, v231, v153
	v_fmac_f32_e32 v182, v232, v154
	v_fmac_f32_e32 v183, v233, v155
	v_fmac_f32_e32 v184, v230, v112
	v_fmac_f32_e32 v185, v231, v113
	v_fmac_f32_e32 v186, v232, v114
	v_fmac_f32_e32 v187, v233, v115
	v_fmac_f32_e32 v224, v230, v104
	v_fmac_f32_e32 v225, v231, v105
	v_fmac_f32_e32 v226, v232, v106
	v_fmac_f32_e32 v227, v233, v107
	v_fmac_f32_e32 v176, v238, v112
	v_fmac_f32_e32 v177, v239, v113
	v_fmac_f32_e32 v178, v240, v114
	v_fmac_f32_e32 v179, v241, v115
	v_fmac_f32_e32 v180, v238, v104
	v_fmac_f32_e32 v181, v239, v105
	v_fmac_f32_e32 v182, v240, v106
	v_fmac_f32_e32 v183, v241, v107
	v_fmac_f32_e32 v184, v238, v96
	v_fmac_f32_e32 v185, v239, v97
	v_fmac_f32_e32 v186, v240, v98
	v_fmac_f32_e32 v187, v241, v99
	v_fmac_f32_e32 v224, v238, v220
	v_fmac_f32_e32 v225, v239, v221
	v_fmac_f32_e32 v226, v240, v222
	v_fmac_f32_e32 v227, v241, v223
	v_add_f32_e32 v176, v242, v176
	v_add_f32_e32 v177, v243, v177
	v_add_f32_e32 v178, v244, v178
	v_add_f32_e32 v179, v245, v179
	v_add_f32_e32 v180, v242, v180
	v_add_f32_e32 v181, v243, v181
	v_add_f32_e32 v182, v244, v182
	v_add_f32_e32 v183, v245, v183
	v_add_f32_e32 v184, v242, v184
	v_add_f32_e32 v185, v243, v185
	v_add_f32_e32 v186, v244, v186
	v_add_f32_e32 v187, v245, v187
	v_add_f32_e32 v224, v242, v224
	v_add_f32_e32 v225, v243, v225
	v_add_f32_e32 v226, v244, v226
	v_add_f32_e32 v227, v245, v227
	v_mov_b32_dpp v216, v100 row_shr:1 row_mask:0xf bank_mask:0xf bound_ctrl:1
	v_mov_b32_dpp v217, v101 row_shr:1 row_mask:0xf bank_mask:0xf bound_ctrl:1
	v_mov_b32_dpp v218, v102 row_shr:1 row_mask:0xf bank_mask:0xf bound_ctrl:1
	v_mov_b32_dpp v219, v103 row_shr:1 row_mask:0xf bank_mask:0xf bound_ctrl:1
	v_mov_b32_dpp v220, v156 row_shl:1 row_mask:0xf bank_mask:0xf bound_ctrl:1
	v_mov_b32_dpp v221, v157 row_shl:1 row_mask:0xf bank_mask:0xf bound_ctrl:1
	v_mov_b32_dpp v222, v158 row_shl:1 row_mask:0xf bank_mask:0xf bound_ctrl:1
	v_mov_b32_dpp v223, v159 row_shl:1 row_mask:0xf bank_mask:0xf bound_ctrl:1
	v_mul_f32_e32 v152, v156, v250
	v_mul_f32_e32 v153, v157, v251
	v_mul_f32_e32 v154, v158, v252
	v_mul_f32_e32 v155, v159, v253
	v_mul_f32_e32 v112, v116, v250
	v_mul_f32_e32 v113, v117, v251
	v_mul_f32_e32 v114, v118, v252
	v_mul_f32_e32 v115, v119, v253
	v_mul_f32_e32 v104, v108, v250
	v_mul_f32_e32 v105, v109, v251
	v_mul_f32_e32 v106, v110, v252
	v_mul_f32_e32 v107, v111, v253
	v_mul_f32_e32 v96, v100, v250
	v_mul_f32_e32 v97, v101, v251
	v_mul_f32_e32 v98, v102, v252
	v_mul_f32_e32 v99, v103, v253
	v_fmac_f32_e32 v152, v246, v216
	v_fmac_f32_e32 v153, v247, v217
	v_fmac_f32_e32 v154, v248, v218
	v_fmac_f32_e32 v155, v249, v219
	v_fmac_f32_e32 v112, v246, v156
	v_fmac_f32_e32 v113, v247, v157
	v_fmac_f32_e32 v114, v248, v158
	v_fmac_f32_e32 v115, v249, v159
	v_fmac_f32_e32 v104, v246, v116
	v_fmac_f32_e32 v105, v247, v117
	v_fmac_f32_e32 v106, v248, v118
	v_fmac_f32_e32 v107, v249, v119
	v_fmac_f32_e32 v96, v246, v108
	v_fmac_f32_e32 v97, v247, v109
	v_fmac_f32_e32 v98, v248, v110
	v_fmac_f32_e32 v99, v249, v111
	s_waitcnt vmcnt(8)
; __device__ __forceinline__ void st_bf4(bf16_t* p, f32x4 v) { u32x2 w; w.x = pk2(v[0], v[1]); w.y = pk2(v[2], v[3]); *(u32x2*)p = w; }
; __device__ __forceinline__ float sigmoidf_(float x) { return __builtin_amdgcn_rcpf(1.f + __expf(-x)); }
; __device__ __forceinline__ float dpp_ror1(float v) { return __int_as_float(__builtin_amdgcn_update_dpp(0, __float_as_int(v), 0x121, 0xf, 0xf, false)); }
; __device__ __forceinline__ float dpp_rol1(float v) { return __int_as_float(__builtin_amdgcn_update_dpp(0, __float_as_int(v), 0x12F, 0xf, 0xf, false)); }
;     __device__ __forceinline__ void tile(const f32x4 (&acc)[2][2][4][2], const Unit& u, int wr, int wc, int fr, int fq) const {
;     ...
;                         const float xv = acc[ai][0][m][n][i], xg = acc[ai][1][m][n][i];
;                         const float uv = m > 0 ? acc[ai][0][m > 0 ? m - 1 : 0][n][i] : 0.f, ug = m > 0 ? acc[ai][1][m > 0 ? m - 1 : 0][n][i] : 0.f;
;                         const float dv = m < 3 ? acc[ai][0][m < 3 ? m + 1 : 3][n][i] : 0.f, dg = m < 3 ? acc[ai][1][m < 3 ? m + 1 : 3][n][i] : 0.f;
;                         const float pv = dpp_ror1(fr == 15 ? uv : xv), pg = dpp_ror1(fr == 15 ? ug : xg);
;                         const float nv = dpp_rol1(fr == 0 ? dv : xv), ng = dpp_rol1(fr == 0 ? dg : xg);
;                         const float yv = wv0[i] * pv + wv1[i] * xv + wv2[i] * nv + bv[i];
;                         const float yg = wg0[i] * pg + wg1[i] * xg + wg2[i] * ng + bg[i];
;                         r[i] = yg * sigmoidf_(yg) * yv;
;                     }
;                     st_bf4(ACT + (size_t)(u.pm * BM + ai * HALF + wr * 64 + m * 16 + fr) * FF + cv, r);
	v_fmac_f32_e32 v152, v120, v116
	v_fmac_f32_e32 v153, v121, v117
	v_fmac_f32_e32 v154, v122, v118
	v_fmac_f32_e32 v155, v123, v119
	v_fmac_f32_e32 v112, v120, v108
	v_fmac_f32_e32 v113, v121, v109
	v_fmac_f32_e32 v114, v122, v110
	v_fmac_f32_e32 v115, v123, v111
	v_fmac_f32_e32 v104, v120, v100
	v_fmac_f32_e32 v105, v121, v101
	v_fmac_f32_e32 v106, v122, v102
	v_fmac_f32_e32 v107, v123, v103
	v_fmac_f32_e32 v96, v120, v220
	v_fmac_f32_e32 v97, v121, v221
	v_fmac_f32_e32 v98, v122, v222
	v_fmac_f32_e32 v99, v123, v223
	v_add_f32_e32 v152, v124, v152
	v_add_f32_e32 v153, v125, v153
	v_add_f32_e32 v154, v126, v154
	v_add_f32_e32 v155, v127, v155
	v_add_f32_e32 v112, v124, v112
	v_add_f32_e32 v113, v125, v113
	v_add_f32_e32 v114, v126, v114
	v_add_f32_e32 v115, v127, v115
	v_add_f32_e32 v104, v124, v104
	v_add_f32_e32 v105, v125, v105
	v_add_f32_e32 v106, v126, v106
	v_add_f32_e32 v107, v127, v107
	v_add_f32_e32 v96, v124, v96
	v_add_f32_e32 v97, v125, v97
	v_add_f32_e32 v98, v126, v98
	v_add_f32_e32 v99, v127, v99
	v_mul_f32_e32 v156, 0xbfb8aa3b, v176
	v_mul_f32_e32 v157, 0xbfb8aa3b, v177
	v_mul_f32_e32 v158, 0xbfb8aa3b, v178
	v_mul_f32_e32 v159, 0xbfb8aa3b, v179
	v_mul_f32_e32 v116, 0xbfb8aa3b, v180
	v_mul_f32_e32 v117, 0xbfb8aa3b, v181
	v_mul_f32_e32 v118, 0xbfb8aa3b, v182
	v_mul_f32_e32 v119, 0xbfb8aa3b, v183
	v_mul_f32_e32 v108, 0xbfb8aa3b, v184
	v_mul_f32_e32 v109, 0xbfb8aa3b, v185
	v_mul_f32_e32 v110, 0xbfb8aa3b, v186
	v_mul_f32_e32 v111, 0xbfb8aa3b, v187
	v_mul_f32_e32 v100, 0xbfb8aa3b, v224
	v_mul_f32_e32 v101, 0xbfb8aa3b, v225
	v_mul_f32_e32 v102, 0xbfb8aa3b, v226
	v_mul_f32_e32 v103, 0xbfb8aa3b, v227
	v_exp_f32_e32 v156, v156
	v_exp_f32_e32 v157, v157
	v_exp_f32_e32 v158, v158
	v_exp_f32_e32 v159, v159
	v_exp_f32_e32 v116, v116
	v_exp_f32_e32 v117, v117
	v_exp_f32_e32 v118, v118
	v_exp_f32_e32 v119, v119
	v_exp_f32_e32 v108, v108
	v_exp_f32_e32 v109, v109
	v_exp_f32_e32 v110, v110
	v_exp_f32_e32 v111, v111
	v_exp_f32_e32 v100, v100
	v_exp_f32_e32 v101, v101
	v_exp_f32_e32 v102, v102
	v_exp_f32_e32 v103, v103
	v_add_f32_e32 v156, 1.0, v156
	v_add_f32_e32 v157, 1.0, v157
	v_add_f32_e32 v158, 1.0, v158
	v_add_f32_e32 v159, 1.0, v159
	v_add_f32_e32 v116, 1.0, v116
	v_add_f32_e32 v117, 1.0, v117
	v_add_f32_e32 v118, 1.0, v118
	v_add_f32_e32 v119, 1.0, v119
	v_add_f32_e32 v108, 1.0, v108
	v_add_f32_e32 v109, 1.0, v109
	v_add_f32_e32 v110, 1.0, v110
	v_add_f32_e32 v111, 1.0, v111
	v_add_f32_e32 v100, 1.0, v100
	v_add_f32_e32 v101, 1.0, v101
	v_add_f32_e32 v102, 1.0, v102
	v_add_f32_e32 v103, 1.0, v103
	v_rcp_f32_e32 v156, v156
	v_rcp_f32_e32 v157, v157
	v_rcp_f32_e32 v158, v158
	v_rcp_f32_e32 v159, v159
	v_rcp_f32_e32 v116, v116
	v_rcp_f32_e32 v117, v117
	v_rcp_f32_e32 v118, v118
	v_rcp_f32_e32 v119, v119
	v_rcp_f32_e32 v108, v108
	v_rcp_f32_e32 v109, v109
	v_rcp_f32_e32 v110, v110
	v_rcp_f32_e32 v111, v111
	v_rcp_f32_e32 v100, v100
	v_rcp_f32_e32 v101, v101
	v_rcp_f32_e32 v102, v102
	v_rcp_f32_e32 v103, v103
	v_mul_f32_e32 v176, v176, v156
	v_mul_f32_e32 v177, v177, v157
	v_mul_f32_e32 v178, v178, v158
	v_mul_f32_e32 v179, v179, v159
	v_mul_f32_e32 v180, v180, v116
	v_mul_f32_e32 v181, v181, v117
	v_mul_f32_e32 v182, v182, v118
	v_mul_f32_e32 v183, v183, v119
	v_mul_f32_e32 v184, v184, v108
	v_mul_f32_e32 v185, v185, v109
	v_mul_f32_e32 v186, v186, v110
	v_mul_f32_e32 v187, v187, v111
	v_mul_f32_e32 v224, v224, v100
	v_mul_f32_e32 v225, v225, v101
	v_mul_f32_e32 v226, v226, v102
	v_mul_f32_e32 v227, v227, v103
	v_mul_f32_e32 v176, v152, v176
	v_mul_f32_e32 v177, v153, v177
	v_mul_f32_e32 v178, v154, v178
	v_mul_f32_e32 v179, v155, v179
	v_mul_f32_e32 v180, v112, v180
	v_mul_f32_e32 v181, v113, v181
	v_mul_f32_e32 v182, v114, v182
	v_mul_f32_e32 v183, v115, v183
	v_mul_f32_e32 v184, v104, v184
	v_mul_f32_e32 v185, v105, v185
	v_mul_f32_e32 v186, v106, v186
	v_mul_f32_e32 v187, v107, v187
	v_mul_f32_e32 v224, v96, v224
	v_mul_f32_e32 v225, v97, v225
	v_mul_f32_e32 v226, v98, v226
	v_mul_f32_e32 v227, v99, v227
	v_cvt_pk_bf16_f32 v156, v176, v177
	v_cvt_pk_bf16_f32 v157, v178, v179
	v_cvt_pk_bf16_f32 v116, v180, v181
	v_cvt_pk_bf16_f32 v117, v182, v183
	v_cvt_pk_bf16_f32 v108, v184, v185
	v_cvt_pk_bf16_f32 v109, v186, v187
	v_cvt_pk_bf16_f32 v100, v224, v225
	v_cvt_pk_bf16_f32 v101, v226, v227
	s_waitcnt vmcnt(4)
	v_mov_b32_dpp v216, v32 row_shr:1 row_mask:0xf bank_mask:0xf bound_ctrl:1
	v_mov_b32_dpp v217, v33 row_shr:1 row_mask:0xf bank_mask:0xf bound_ctrl:1
	v_mov_b32_dpp v218, v34 row_shr:1 row_mask:0xf bank_mask:0xf bound_ctrl:1
	v_mov_b32_dpp v219, v35 row_shr:1 row_mask:0xf bank_mask:0xf bound_ctrl:1
	v_mov_b32_dpp v220, v56 row_shl:1 row_mask:0xf bank_mask:0xf bound_ctrl:1
	v_mov_b32_dpp v221, v57 row_shl:1 row_mask:0xf bank_mask:0xf bound_ctrl:1
	v_mov_b32_dpp v222, v58 row_shl:1 row_mask:0xf bank_mask:0xf bound_ctrl:1
	v_mov_b32_dpp v223, v59 row_shl:1 row_mask:0xf bank_mask:0xf bound_ctrl:1
	v_mul_f32_e32 v176, v56, v132
	v_mul_f32_e32 v177, v57, v133
	v_mul_f32_e32 v178, v58, v134
	v_mul_f32_e32 v179, v59, v135
	v_mul_f32_e32 v180, v48, v132
	v_mul_f32_e32 v181, v49, v133
	v_mul_f32_e32 v182, v50, v134
	v_mul_f32_e32 v183, v51, v135
	v_mul_f32_e32 v184, v40, v132
	v_mul_f32_e32 v185, v41, v133
	v_mul_f32_e32 v186, v42, v134
	v_mul_f32_e32 v187, v43, v135
	v_mul_f32_e32 v224, v32, v132
	v_mul_f32_e32 v225, v33, v133
	v_mul_f32_e32 v226, v34, v134
	v_mul_f32_e32 v227, v35, v135
	v_fmac_f32_e32 v176, v128, v216
	v_fmac_f32_e32 v177, v129, v217
	v_fmac_f32_e32 v178, v130, v218
	v_fmac_f32_e32 v179, v131, v219
	v_fmac_f32_e32 v180, v128, v56
	v_fmac_f32_e32 v181, v129, v57
	v_fmac_f32_e32 v182, v130, v58
	v_fmac_f32_e32 v183, v131, v59
	v_fmac_f32_e32 v184, v128, v48
	v_fmac_f32_e32 v185, v129, v49
	v_fmac_f32_e32 v186, v130, v50
	v_fmac_f32_e32 v187, v131, v51
	v_fmac_f32_e32 v224, v128, v40
	v_fmac_f32_e32 v225, v129, v41
	v_fmac_f32_e32 v226, v130, v42
	v_fmac_f32_e32 v227, v131, v43
	v_fmac_f32_e32 v176, v136, v48
	v_fmac_f32_e32 v177, v137, v49
	v_fmac_f32_e32 v178, v138, v50
	v_fmac_f32_e32 v179, v139, v51
	v_fmac_f32_e32 v180, v136, v40
	v_fmac_f32_e32 v181, v137, v41
	v_fmac_f32_e32 v182, v138, v42
	v_fmac_f32_e32 v183, v139, v43
	v_fmac_f32_e32 v184, v136, v32
	v_fmac_f32_e32 v185, v137, v33
	v_fmac_f32_e32 v186, v138, v34
	v_fmac_f32_e32 v187, v139, v35
	v_fmac_f32_e32 v224, v136, v220
	v_fmac_f32_e32 v225, v137, v221
	v_fmac_f32_e32 v226, v138, v222
	v_fmac_f32_e32 v227, v139, v223
	v_add_f32_e32 v176, v140, v176
	v_add_f32_e32 v177, v141, v177
	v_add_f32_e32 v178, v142, v178
	v_add_f32_e32 v179, v143, v179
	v_add_f32_e32 v180, v140, v180
	v_add_f32_e32 v181, v141, v181
	v_add_f32_e32 v182, v142, v182
	v_add_f32_e32 v183, v143, v183
	v_add_f32_e32 v184, v140, v184
	v_add_f32_e32 v185, v141, v185
	v_add_f32_e32 v186, v142, v186
	v_add_f32_e32 v187, v143, v187
	v_add_f32_e32 v224, v140, v224
	v_add_f32_e32 v225, v141, v225
	v_add_f32_e32 v226, v142, v226
	v_add_f32_e32 v227, v143, v227
	s_waitcnt vmcnt(0)
; __device__ __forceinline__ float sigmoidf_(float x) { return __builtin_amdgcn_rcpf(1.f + __expf(-x)); }
; __device__ __forceinline__ float dpp_ror1(float v) { return __int_as_float(__builtin_amdgcn_update_dpp(0, __float_as_int(v), 0x121, 0xf, 0xf, false)); }
; __device__ __forceinline__ float dpp_rol1(float v) { return __int_as_float(__builtin_amdgcn_update_dpp(0, __float_as_int(v), 0x12F, 0xf, 0xf, false)); }
;     __device__ __forceinline__ void tile(const f32x4 (&acc)[2][2][4][2], const Unit& u, int wr, int wc, int fr, int fq) const {
;     ...
;                         const float xv = acc[ai][0][m][n][i], xg = acc[ai][1][m][n][i];
;                         const float uv = m > 0 ? acc[ai][0][m > 0 ? m - 1 : 0][n][i] : 0.f, ug = m > 0 ? acc[ai][1][m > 0 ? m - 1 : 0][n][i] : 0.f;
;                         const float dv = m < 3 ? acc[ai][0][m < 3 ? m + 1 : 3][n][i] : 0.f, dg = m < 3 ? acc[ai][1][m < 3 ? m + 1 : 3][n][i] : 0.f;
;                         const float pv = dpp_ror1(fr == 15 ? uv : xv), pg = dpp_ror1(fr == 15 ? ug : xg);
;                         const float nv = dpp_rol1(fr == 0 ? dv : xv), ng = dpp_rol1(fr == 0 ? dg : xg);
;                         const float yv = wv0[i] * pv + wv1[i] * xv + wv2[i] * nv + bv[i];
;                         const float yg = wg0[i] * pg + wg1[i] * xg + wg2[i] * ng + bg[i];
;                         r[i] = yg * sigmoidf_(yg) * yv;
	v_mov_b32_dpp v216, v36 row_shr:1 row_mask:0xf bank_mask:0xf bound_ctrl:1
	v_mov_b32_dpp v217, v37 row_shr:1 row_mask:0xf bank_mask:0xf bound_ctrl:1
	v_mov_b32_dpp v218, v38 row_shr:1 row_mask:0xf bank_mask:0xf bound_ctrl:1
	v_mov_b32_dpp v219, v39 row_shr:1 row_mask:0xf bank_mask:0xf bound_ctrl:1
	v_mov_b32_dpp v220, v60 row_shl:1 row_mask:0xf bank_mask:0xf bound_ctrl:1
	v_mov_b32_dpp v221, v61 row_shl:1 row_mask:0xf bank_mask:0xf bound_ctrl:1
	v_mov_b32_dpp v222, v62 row_shl:1 row_mask:0xf bank_mask:0xf bound_ctrl:1
	v_mov_b32_dpp v223, v63 row_shl:1 row_mask:0xf bank_mask:0xf bound_ctrl:1
	v_mul_f32_e32 v56, v60, v148
	v_mul_f32_e32 v57, v61, v149
	v_mul_f32_e32 v58, v62, v150
	v_mul_f32_e32 v59, v63, v151
	v_mul_f32_e32 v48, v52, v148
	v_mul_f32_e32 v49, v53, v149
	v_mul_f32_e32 v50, v54, v150
	v_mul_f32_e32 v51, v55, v151
	v_mul_f32_e32 v40, v44, v148
	v_mul_f32_e32 v41, v45, v149
	v_mul_f32_e32 v42, v46, v150
	v_mul_f32_e32 v43, v47, v151
	v_mul_f32_e32 v32, v36, v148
	v_mul_f32_e32 v33, v37, v149
	v_mul_f32_e32 v34, v38, v150
	v_mul_f32_e32 v35, v39, v151
	v_fmac_f32_e32 v56, v144, v216
	v_fmac_f32_e32 v57, v145, v217
	v_fmac_f32_e32 v58, v146, v218
	v_fmac_f32_e32 v59, v147, v219
	v_fmac_f32_e32 v48, v144, v60
	v_fmac_f32_e32 v49, v145, v61
	v_fmac_f32_e32 v50, v146, v62
	v_fmac_f32_e32 v51, v147, v63
	v_fmac_f32_e32 v40, v144, v52
	v_fmac_f32_e32 v41, v145, v53
	v_fmac_f32_e32 v42, v146, v54
	v_fmac_f32_e32 v43, v147, v55
	v_fmac_f32_e32 v32, v144, v44
	v_fmac_f32_e32 v33, v145, v45
	v_fmac_f32_e32 v34, v146, v46
	v_fmac_f32_e32 v35, v147, v47
	v_fmac_f32_e32 v56, v208, v52
	v_fmac_f32_e32 v57, v209, v53
	v_fmac_f32_e32 v58, v210, v54
	v_fmac_f32_e32 v59, v211, v55
	v_fmac_f32_e32 v48, v208, v44
	v_fmac_f32_e32 v49, v209, v45
	v_fmac_f32_e32 v50, v210, v46
	v_fmac_f32_e32 v51, v211, v47
	v_fmac_f32_e32 v40, v208, v36
	v_fmac_f32_e32 v41, v209, v37
	v_fmac_f32_e32 v42, v210, v38
	v_fmac_f32_e32 v43, v211, v39
	v_fmac_f32_e32 v32, v208, v220
	v_fmac_f32_e32 v33, v209, v221
	v_fmac_f32_e32 v34, v210, v222
	v_fmac_f32_e32 v35, v211, v223
	v_add_f32_e32 v56, v212, v56
	v_add_f32_e32 v57, v213, v57
	v_add_f32_e32 v58, v214, v58
	v_add_f32_e32 v59, v215, v59
	v_add_f32_e32 v48, v212, v48
	v_add_f32_e32 v49, v213, v49
	v_add_f32_e32 v50, v214, v50
	v_add_f32_e32 v51, v215, v51
	v_add_f32_e32 v40, v212, v40
	v_add_f32_e32 v41, v213, v41
	v_add_f32_e32 v42, v214, v42
	v_add_f32_e32 v43, v215, v43
	v_add_f32_e32 v32, v212, v32
	v_add_f32_e32 v33, v213, v33
	v_add_f32_e32 v34, v214, v34
	v_add_f32_e32 v35, v215, v35
	v_mul_f32_e32 v60, 0xbfb8aa3b, v176
	v_mul_f32_e32 v61, 0xbfb8aa3b, v177
	v_mul_f32_e32 v62, 0xbfb8aa3b, v178
	v_mul_f32_e32 v63, 0xbfb8aa3b, v179
	v_mul_f32_e32 v52, 0xbfb8aa3b, v180
	v_mul_f32_e32 v53, 0xbfb8aa3b, v181
	v_mul_f32_e32 v54, 0xbfb8aa3b, v182
	v_mul_f32_e32 v55, 0xbfb8aa3b, v183
	v_mul_f32_e32 v44, 0xbfb8aa3b, v184
	v_mul_f32_e32 v45, 0xbfb8aa3b, v185
	v_mul_f32_e32 v46, 0xbfb8aa3b, v186
	v_mul_f32_e32 v47, 0xbfb8aa3b, v187
	v_mul_f32_e32 v36, 0xbfb8aa3b, v224
	v_mul_f32_e32 v37, 0xbfb8aa3b, v225
	v_mul_f32_e32 v38, 0xbfb8aa3b, v226
	v_mul_f32_e32 v39, 0xbfb8aa3b, v227
	v_exp_f32_e32 v60, v60
	v_exp_f32_e32 v61, v61
	v_exp_f32_e32 v62, v62
	v_exp_f32_e32 v63, v63
	v_exp_f32_e32 v52, v52
	v_exp_f32_e32 v53, v53
	v_exp_f32_e32 v54, v54
	v_exp_f32_e32 v55, v55
	v_exp_f32_e32 v44, v44
	v_exp_f32_e32 v45, v45
	v_exp_f32_e32 v46, v46
	v_exp_f32_e32 v47, v47
	v_exp_f32_e32 v36, v36
	v_exp_f32_e32 v37, v37
	v_exp_f32_e32 v38, v38
	v_exp_f32_e32 v39, v39
	v_add_f32_e32 v60, 1.0, v60
	v_add_f32_e32 v61, 1.0, v61
	v_add_f32_e32 v62, 1.0, v62
	v_add_f32_e32 v63, 1.0, v63
	v_add_f32_e32 v52, 1.0, v52
	v_add_f32_e32 v53, 1.0, v53
	v_add_f32_e32 v54, 1.0, v54
	v_add_f32_e32 v55, 1.0, v55
	v_add_f32_e32 v44, 1.0, v44
	v_add_f32_e32 v45, 1.0, v45
	v_add_f32_e32 v46, 1.0, v46
	v_add_f32_e32 v47, 1.0, v47
	v_add_f32_e32 v36, 1.0, v36
	v_add_f32_e32 v37, 1.0, v37
	v_add_f32_e32 v38, 1.0, v38
	v_add_f32_e32 v39, 1.0, v39
	v_rcp_f32_e32 v60, v60
	v_rcp_f32_e32 v61, v61
	v_rcp_f32_e32 v62, v62
	v_rcp_f32_e32 v63, v63
	v_rcp_f32_e32 v52, v52
	v_rcp_f32_e32 v53, v53
	v_rcp_f32_e32 v54, v54
	v_rcp_f32_e32 v55, v55
	v_rcp_f32_e32 v44, v44
	v_rcp_f32_e32 v45, v45
	v_rcp_f32_e32 v46, v46
	v_rcp_f32_e32 v47, v47
	v_rcp_f32_e32 v36, v36
	v_rcp_f32_e32 v37, v37
	v_rcp_f32_e32 v38, v38
	v_rcp_f32_e32 v39, v39
	v_mul_f32_e32 v176, v176, v60
	v_mul_f32_e32 v177, v177, v61
	v_mul_f32_e32 v178, v178, v62
	v_mul_f32_e32 v179, v179, v63
	v_mul_f32_e32 v180, v180, v52
	v_mul_f32_e32 v181, v181, v53
	v_mul_f32_e32 v182, v182, v54
	v_mul_f32_e32 v183, v183, v55
	v_mul_f32_e32 v184, v184, v44
	v_mul_f32_e32 v185, v185, v45
	v_mul_f32_e32 v186, v186, v46
	v_mul_f32_e32 v187, v187, v47
	v_mul_f32_e32 v224, v224, v36
	v_mul_f32_e32 v225, v225, v37
	v_mul_f32_e32 v226, v226, v38
	v_mul_f32_e32 v227, v227, v39
	v_mul_f32_e32 v176, v56, v176
	v_mul_f32_e32 v177, v57, v177
	v_mul_f32_e32 v178, v58, v178
	v_mul_f32_e32 v179, v59, v179
	v_mul_f32_e32 v180, v48, v180
	v_mul_f32_e32 v181, v49, v181
	v_mul_f32_e32 v182, v50, v182
	v_mul_f32_e32 v183, v51, v183
	v_mul_f32_e32 v184, v40, v184
	v_mul_f32_e32 v185, v41, v185
	v_mul_f32_e32 v186, v42, v186
	v_mul_f32_e32 v187, v43, v187
	v_mul_f32_e32 v224, v32, v224
	v_mul_f32_e32 v225, v33, v225
	v_mul_f32_e32 v226, v34, v226
	v_mul_f32_e32 v227, v35, v227
	v_cvt_pk_bf16_f32 v158, v176, v177
	v_cvt_pk_bf16_f32 v159, v178, v179
	v_cvt_pk_bf16_f32 v118, v180, v181
	v_cvt_pk_bf16_f32 v119, v182, v183
	v_cvt_pk_bf16_f32 v110, v184, v185
	v_cvt_pk_bf16_f32 v111, v186, v187
	v_cvt_pk_bf16_f32 v102, v224, v225
; __device__ __forceinline__ void st_bf4(bf16_t* p, f32x4 v) { u32x2 w; w.x = pk2(v[0], v[1]); w.y = pk2(v[2], v[3]); *(u32x2*)p = w; }
; __device__ __forceinline__ float sigmoidf_(float x) { return __builtin_amdgcn_rcpf(1.f + __expf(-x)); }
; __device__ __forceinline__ float dpp_ror1(float v) { return __int_as_float(__builtin_amdgcn_update_dpp(0, __float_as_int(v), 0x121, 0xf, 0xf, false)); }
; __device__ __forceinline__ float dpp_rol1(float v) { return __int_as_float(__builtin_amdgcn_update_dpp(0, __float_as_int(v), 0x12F, 0xf, 0xf, false)); }
;     __device__ __forceinline__ void tile(const f32x4 (&acc)[2][2][4][2], const Unit& u, int wr, int wc, int fr, int fq) const {
;     ...
;                         const float xv = acc[ai][0][m][n][i], xg = acc[ai][1][m][n][i];
;                         const float uv = m > 0 ? acc[ai][0][m > 0 ? m - 1 : 0][n][i] : 0.f, ug = m > 0 ? acc[ai][1][m > 0 ? m - 1 : 0][n][i] : 0.f;
;                         const float dv = m < 3 ? acc[ai][0][m < 3 ? m + 1 : 3][n][i] : 0.f, dg = m < 3 ? acc[ai][1][m < 3 ? m + 1 : 3][n][i] : 0.f;
;                         const float pv = dpp_ror1(fr == 15 ? uv : xv), pg = dpp_ror1(fr == 15 ? ug : xg);
;                         const float nv = dpp_rol1(fr == 0 ? dv : xv), ng = dpp_rol1(fr == 0 ? dg : xg);
;                         const float yv = wv0[i] * pv + wv1[i] * xv + wv2[i] * nv + bv[i];
;                         const float yg = wg0[i] * pg + wg1[i] * xg + wg2[i] * ng + bg[i];
;                         r[i] = yg * sigmoidf_(yg) * yv;
;                     }
;                     st_bf4(ACT + (size_t)(u.pm * BM + ai * HALF + wr * 64 + m * 16 + fr) * FF + cv, r);
	v_cvt_pk_bf16_f32 v103, v226, v227
	s_nop 1
	v_permlane16_swap_b32_e32 v156, v158
	v_permlane16_swap_b32_e32 v157, v159
	v_permlane16_swap_b32_e32 v116, v118
	v_permlane16_swap_b32_e32 v117, v119
	v_permlane16_swap_b32_e32 v108, v110
	v_permlane16_swap_b32_e32 v109, v111
	v_permlane16_swap_b32_e32 v100, v102
	v_permlane16_swap_b32_e32 v101, v103
	global_store_dwordx4 v173, v[156:159], s[0:1]
	v_add_u32_e32 v175, 0x2c00, v173
	global_store_dwordx4 v175, v[116:119], s[0:1]
	v_add_u32_e32 v175, 0x5800, v173
	global_store_dwordx4 v175, v[108:111], s[0:1]
	v_add_u32_e32 v175, 0x8400, v173
	global_store_dwordx4 v175, v[100:103], s[0:1]
	v_mov_b32_dpp v216, v64 row_shr:1 row_mask:0xf bank_mask:0xf bound_ctrl:1
	v_mov_b32_dpp v217, v65 row_shr:1 row_mask:0xf bank_mask:0xf bound_ctrl:1
	v_mov_b32_dpp v218, v66 row_shr:1 row_mask:0xf bank_mask:0xf bound_ctrl:1
	v_mov_b32_dpp v219, v67 row_shr:1 row_mask:0xf bank_mask:0xf bound_ctrl:1
	v_mov_b32_dpp v220, v88 row_shl:1 row_mask:0xf bank_mask:0xf bound_ctrl:1
	v_mov_b32_dpp v221, v89 row_shl:1 row_mask:0xf bank_mask:0xf bound_ctrl:1
	v_mov_b32_dpp v222, v90 row_shl:1 row_mask:0xf bank_mask:0xf bound_ctrl:1
	v_mov_b32_dpp v223, v91 row_shl:1 row_mask:0xf bank_mask:0xf bound_ctrl:1
	v_mul_f32_e32 v176, v88, v234
	v_mul_f32_e32 v177, v89, v235
	v_mul_f32_e32 v178, v90, v236
	v_mul_f32_e32 v179, v91, v237
	v_mul_f32_e32 v180, v80, v234
	v_mul_f32_e32 v181, v81, v235
	v_mul_f32_e32 v182, v82, v236
	v_mul_f32_e32 v183, v83, v237
	v_mul_f32_e32 v184, v72, v234
	v_mul_f32_e32 v185, v73, v235
	v_mul_f32_e32 v186, v74, v236
	v_mul_f32_e32 v187, v75, v237
	v_mul_f32_e32 v224, v64, v234
	v_mul_f32_e32 v225, v65, v235
	v_mul_f32_e32 v226, v66, v236
	v_mul_f32_e32 v227, v67, v237
	v_fmac_f32_e32 v176, v230, v216
	v_fmac_f32_e32 v177, v231, v217
	v_fmac_f32_e32 v178, v232, v218
	v_fmac_f32_e32 v179, v233, v219
	v_fmac_f32_e32 v180, v230, v88
	v_fmac_f32_e32 v181, v231, v89
	v_fmac_f32_e32 v182, v232, v90
	v_fmac_f32_e32 v183, v233, v91
	v_fmac_f32_e32 v184, v230, v80
	v_fmac_f32_e32 v185, v231, v81
	v_fmac_f32_e32 v186, v232, v82
	v_fmac_f32_e32 v187, v233, v83
	v_fmac_f32_e32 v224, v230, v72
	v_fmac_f32_e32 v225, v231, v73
	v_fmac_f32_e32 v226, v232, v74
	v_fmac_f32_e32 v227, v233, v75
	v_fmac_f32_e32 v176, v238, v80
	v_fmac_f32_e32 v177, v239, v81
	v_fmac_f32_e32 v178, v240, v82
	v_fmac_f32_e32 v179, v241, v83
	v_fmac_f32_e32 v180, v238, v72
	v_fmac_f32_e32 v181, v239, v73
	v_fmac_f32_e32 v182, v240, v74
	v_fmac_f32_e32 v183, v241, v75
	v_fmac_f32_e32 v184, v238, v64
	v_fmac_f32_e32 v185, v239, v65
	v_fmac_f32_e32 v186, v240, v66
	v_fmac_f32_e32 v187, v241, v67
	v_fmac_f32_e32 v224, v238, v220
	v_fmac_f32_e32 v225, v239, v221
	v_fmac_f32_e32 v226, v240, v222
	v_fmac_f32_e32 v227, v241, v223
	v_add_f32_e32 v176, v242, v176
	v_add_f32_e32 v177, v243, v177
	v_add_f32_e32 v178, v244, v178
	v_add_f32_e32 v179, v245, v179
	v_add_f32_e32 v180, v242, v180
	v_add_f32_e32 v181, v243, v181
	v_add_f32_e32 v182, v244, v182
	v_add_f32_e32 v183, v245, v183
	v_add_f32_e32 v184, v242, v184
	v_add_f32_e32 v185, v243, v185
	v_add_f32_e32 v186, v244, v186
	v_add_f32_e32 v187, v245, v187
	v_add_f32_e32 v224, v242, v224
	v_add_f32_e32 v225, v243, v225
	v_add_f32_e32 v226, v244, v226
	v_add_f32_e32 v227, v245, v227
	v_mov_b32_dpp v216, v68 row_shr:1 row_mask:0xf bank_mask:0xf bound_ctrl:1
	v_mov_b32_dpp v217, v69 row_shr:1 row_mask:0xf bank_mask:0xf bound_ctrl:1
	v_mov_b32_dpp v218, v70 row_shr:1 row_mask:0xf bank_mask:0xf bound_ctrl:1
	v_mov_b32_dpp v219, v71 row_shr:1 row_mask:0xf bank_mask:0xf bound_ctrl:1
	v_mov_b32_dpp v220, v92 row_shl:1 row_mask:0xf bank_mask:0xf bound_ctrl:1
	v_mov_b32_dpp v221, v93 row_shl:1 row_mask:0xf bank_mask:0xf bound_ctrl:1
	v_mov_b32_dpp v222, v94 row_shl:1 row_mask:0xf bank_mask:0xf bound_ctrl:1
	v_mov_b32_dpp v223, v95 row_shl:1 row_mask:0xf bank_mask:0xf bound_ctrl:1
	v_mul_f32_e32 v88, v92, v250
	v_mul_f32_e32 v89, v93, v251
	v_mul_f32_e32 v90, v94, v252
	v_mul_f32_e32 v91, v95, v253
	v_mul_f32_e32 v80, v84, v250
	v_mul_f32_e32 v81, v85, v251
	v_mul_f32_e32 v82, v86, v252
	v_mul_f32_e32 v83, v87, v253
	v_mul_f32_e32 v72, v76, v250
	v_mul_f32_e32 v73, v77, v251
	v_mul_f32_e32 v74, v78, v252
	v_mul_f32_e32 v75, v79, v253
	v_mul_f32_e32 v64, v68, v250
	v_mul_f32_e32 v65, v69, v251
	v_mul_f32_e32 v66, v70, v252
	v_mul_f32_e32 v67, v71, v253
	v_fmac_f32_e32 v88, v246, v216
	v_fmac_f32_e32 v89, v247, v217
	v_fmac_f32_e32 v90, v248, v218
	v_fmac_f32_e32 v91, v249, v219
	v_fmac_f32_e32 v80, v246, v92
	v_fmac_f32_e32 v81, v247, v93
	v_fmac_f32_e32 v82, v248, v94
	v_fmac_f32_e32 v83, v249, v95
	v_fmac_f32_e32 v72, v246, v84
	v_fmac_f32_e32 v73, v247, v85
	v_fmac_f32_e32 v74, v248, v86
	v_fmac_f32_e32 v75, v249, v87
	v_fmac_f32_e32 v64, v246, v76
	v_fmac_f32_e32 v65, v247, v77
	v_fmac_f32_e32 v66, v248, v78
	v_fmac_f32_e32 v67, v249, v79
	v_fmac_f32_e32 v88, v120, v84
	v_fmac_f32_e32 v89, v121, v85
	v_fmac_f32_e32 v90, v122, v86
	v_fmac_f32_e32 v91, v123, v87
	v_fmac_f32_e32 v80, v120, v76
	v_fmac_f32_e32 v81, v121, v77
	v_fmac_f32_e32 v82, v122, v78
	v_fmac_f32_e32 v83, v123, v79
	v_fmac_f32_e32 v72, v120, v68
	v_fmac_f32_e32 v73, v121, v69
	v_fmac_f32_e32 v74, v122, v70
	v_fmac_f32_e32 v75, v123, v71
	v_fmac_f32_e32 v64, v120, v220
	v_fmac_f32_e32 v65, v121, v221
	v_fmac_f32_e32 v66, v122, v222
	v_fmac_f32_e32 v67, v123, v223
	v_add_f32_e32 v88, v124, v88
	v_add_f32_e32 v89, v125, v89
	v_add_f32_e32 v90, v126, v90
	v_add_f32_e32 v91, v127, v91
	v_add_f32_e32 v80, v124, v80
	v_add_f32_e32 v81, v125, v81
	v_add_f32_e32 v82, v126, v82
	v_add_f32_e32 v83, v127, v83
	v_add_f32_e32 v72, v124, v72
; __device__ __forceinline__ float sigmoidf_(float x) { return __builtin_amdgcn_rcpf(1.f + __expf(-x)); }
; __device__ __forceinline__ float dpp_ror1(float v) { return __int_as_float(__builtin_amdgcn_update_dpp(0, __float_as_int(v), 0x121, 0xf, 0xf, false)); }
; __device__ __forceinline__ float dpp_rol1(float v) { return __int_as_float(__builtin_amdgcn_update_dpp(0, __float_as_int(v), 0x12F, 0xf, 0xf, false)); }
;     __device__ __forceinline__ void tile(const f32x4 (&acc)[2][2][4][2], const Unit& u, int wr, int wc, int fr, int fq) const {
;     ...
;                         const float xv = acc[ai][0][m][n][i], xg = acc[ai][1][m][n][i];
;                         const float uv = m > 0 ? acc[ai][0][m > 0 ? m - 1 : 0][n][i] : 0.f, ug = m > 0 ? acc[ai][1][m > 0 ? m - 1 : 0][n][i] : 0.f;
;                         const float dv = m < 3 ? acc[ai][0][m < 3 ? m + 1 : 3][n][i] : 0.f, dg = m < 3 ? acc[ai][1][m < 3 ? m + 1 : 3][n][i] : 0.f;
;                         const float pv = dpp_ror1(fr == 15 ? uv : xv), pg = dpp_ror1(fr == 15 ? ug : xg);
;                         const float nv = dpp_rol1(fr == 0 ? dv : xv), ng = dpp_rol1(fr == 0 ? dg : xg);
;                         const float yv = wv0[i] * pv + wv1[i] * xv + wv2[i] * nv + bv[i];
;                         const float yg = wg0[i] * pg + wg1[i] * xg + wg2[i] * ng + bg[i];
;                         r[i] = yg * sigmoidf_(yg) * yv;
	v_add_f32_e32 v73, v125, v73
	v_add_f32_e32 v74, v126, v74
	v_add_f32_e32 v75, v127, v75
	v_add_f32_e32 v64, v124, v64
	v_add_f32_e32 v65, v125, v65
	v_add_f32_e32 v66, v126, v66
	v_add_f32_e32 v67, v127, v67
	v_mul_f32_e32 v92, 0xbfb8aa3b, v176
	v_mul_f32_e32 v93, 0xbfb8aa3b, v177
	v_mul_f32_e32 v94, 0xbfb8aa3b, v178
	v_mul_f32_e32 v95, 0xbfb8aa3b, v179
	v_mul_f32_e32 v84, 0xbfb8aa3b, v180
	v_mul_f32_e32 v85, 0xbfb8aa3b, v181
	v_mul_f32_e32 v86, 0xbfb8aa3b, v182
	v_mul_f32_e32 v87, 0xbfb8aa3b, v183
	v_mul_f32_e32 v76, 0xbfb8aa3b, v184
	v_mul_f32_e32 v77, 0xbfb8aa3b, v185
	v_mul_f32_e32 v78, 0xbfb8aa3b, v186
	v_mul_f32_e32 v79, 0xbfb8aa3b, v187
	v_mul_f32_e32 v68, 0xbfb8aa3b, v224
	v_mul_f32_e32 v69, 0xbfb8aa3b, v225
	v_mul_f32_e32 v70, 0xbfb8aa3b, v226
	v_mul_f32_e32 v71, 0xbfb8aa3b, v227
	v_exp_f32_e32 v92, v92
	v_exp_f32_e32 v93, v93
	v_exp_f32_e32 v94, v94
	v_exp_f32_e32 v95, v95
	v_exp_f32_e32 v84, v84
	v_exp_f32_e32 v85, v85
	v_exp_f32_e32 v86, v86
	v_exp_f32_e32 v87, v87
	v_exp_f32_e32 v76, v76
	v_exp_f32_e32 v77, v77
	v_exp_f32_e32 v78, v78
	v_exp_f32_e32 v79, v79
	v_exp_f32_e32 v68, v68
	v_exp_f32_e32 v69, v69
	v_exp_f32_e32 v70, v70
	v_exp_f32_e32 v71, v71
	v_add_f32_e32 v92, 1.0, v92
	v_add_f32_e32 v93, 1.0, v93
	v_add_f32_e32 v94, 1.0, v94
	v_add_f32_e32 v95, 1.0, v95
	v_add_f32_e32 v84, 1.0, v84
	v_add_f32_e32 v85, 1.0, v85
	v_add_f32_e32 v86, 1.0, v86
	v_add_f32_e32 v87, 1.0, v87
	v_add_f32_e32 v76, 1.0, v76
	v_add_f32_e32 v77, 1.0, v77
	v_add_f32_e32 v78, 1.0, v78
	v_add_f32_e32 v79, 1.0, v79
	v_add_f32_e32 v68, 1.0, v68
	v_add_f32_e32 v69, 1.0, v69
	v_add_f32_e32 v70, 1.0, v70
	v_add_f32_e32 v71, 1.0, v71
	v_rcp_f32_e32 v92, v92
	v_rcp_f32_e32 v93, v93
	v_rcp_f32_e32 v94, v94
	v_rcp_f32_e32 v95, v95
	v_rcp_f32_e32 v84, v84
	v_rcp_f32_e32 v85, v85
	v_rcp_f32_e32 v86, v86
	v_rcp_f32_e32 v87, v87
	v_rcp_f32_e32 v76, v76
	v_rcp_f32_e32 v77, v77
	v_rcp_f32_e32 v78, v78
	v_rcp_f32_e32 v79, v79
	v_rcp_f32_e32 v68, v68
	v_rcp_f32_e32 v69, v69
	v_rcp_f32_e32 v70, v70
	v_rcp_f32_e32 v71, v71
	v_mul_f32_e32 v176, v176, v92
	v_mul_f32_e32 v177, v177, v93
	v_mul_f32_e32 v178, v178, v94
	v_mul_f32_e32 v179, v179, v95
	v_mul_f32_e32 v180, v180, v84
	v_mul_f32_e32 v181, v181, v85
	v_mul_f32_e32 v182, v182, v86
	v_mul_f32_e32 v183, v183, v87
	v_mul_f32_e32 v184, v184, v76
	v_mul_f32_e32 v185, v185, v77
	v_mul_f32_e32 v186, v186, v78
	v_mul_f32_e32 v187, v187, v79
	v_mul_f32_e32 v224, v224, v68
	v_mul_f32_e32 v225, v225, v69
	v_mul_f32_e32 v226, v226, v70
	v_mul_f32_e32 v227, v227, v71
	v_mul_f32_e32 v176, v88, v176
	v_mul_f32_e32 v177, v89, v177
	v_mul_f32_e32 v178, v90, v178
	v_mul_f32_e32 v179, v91, v179
	v_mul_f32_e32 v180, v80, v180
	v_mul_f32_e32 v181, v81, v181
	v_mul_f32_e32 v182, v82, v182
	v_mul_f32_e32 v183, v83, v183
	v_mul_f32_e32 v184, v72, v184
	v_mul_f32_e32 v185, v73, v185
	v_mul_f32_e32 v186, v74, v186
	v_mul_f32_e32 v187, v75, v187
	v_mul_f32_e32 v224, v64, v224
	v_mul_f32_e32 v225, v65, v225
	v_mul_f32_e32 v226, v66, v226
	v_mul_f32_e32 v227, v67, v227
	v_cvt_pk_bf16_f32 v92, v176, v177
	v_cvt_pk_bf16_f32 v93, v178, v179
	v_cvt_pk_bf16_f32 v84, v180, v181
	v_cvt_pk_bf16_f32 v85, v182, v183
	v_cvt_pk_bf16_f32 v76, v184, v185
	v_cvt_pk_bf16_f32 v77, v186, v187
	v_cvt_pk_bf16_f32 v68, v224, v225
	v_cvt_pk_bf16_f32 v69, v226, v227
	v_mov_b32_dpp v216, v0 row_shr:1 row_mask:0xf bank_mask:0xf bound_ctrl:1
	v_mov_b32_dpp v217, v1 row_shr:1 row_mask:0xf bank_mask:0xf bound_ctrl:1
	v_mov_b32_dpp v218, v2 row_shr:1 row_mask:0xf bank_mask:0xf bound_ctrl:1
	v_mov_b32_dpp v219, v3 row_shr:1 row_mask:0xf bank_mask:0xf bound_ctrl:1
	v_mov_b32_dpp v220, v24 row_shl:1 row_mask:0xf bank_mask:0xf bound_ctrl:1
	v_mov_b32_dpp v221, v25 row_shl:1 row_mask:0xf bank_mask:0xf bound_ctrl:1
	v_mov_b32_dpp v222, v26 row_shl:1 row_mask:0xf bank_mask:0xf bound_ctrl:1
	v_mov_b32_dpp v223, v27 row_shl:1 row_mask:0xf bank_mask:0xf bound_ctrl:1
	v_mul_f32_e32 v176, v24, v132
	v_mul_f32_e32 v177, v25, v133
	v_mul_f32_e32 v178, v26, v134
	v_mul_f32_e32 v179, v27, v135
	v_mul_f32_e32 v180, v16, v132
	v_mul_f32_e32 v181, v17, v133
	v_mul_f32_e32 v182, v18, v134
	v_mul_f32_e32 v183, v19, v135
	v_mul_f32_e32 v184, v8, v132
	v_mul_f32_e32 v185, v9, v133
	v_mul_f32_e32 v186, v10, v134
	v_mul_f32_e32 v187, v11, v135
	v_mul_f32_e32 v224, v0, v132
	v_mul_f32_e32 v225, v1, v133
	v_mul_f32_e32 v226, v2, v134
	v_mul_f32_e32 v227, v3, v135
	v_fmac_f32_e32 v176, v128, v216
	v_fmac_f32_e32 v177, v129, v217
	v_fmac_f32_e32 v178, v130, v218
	v_fmac_f32_e32 v179, v131, v219
	v_fmac_f32_e32 v180, v128, v24
	v_fmac_f32_e32 v181, v129, v25
	v_fmac_f32_e32 v182, v130, v26
	v_fmac_f32_e32 v183, v131, v27
	v_fmac_f32_e32 v184, v128, v16
	v_fmac_f32_e32 v185, v129, v17
	v_fmac_f32_e32 v186, v130, v18
	v_fmac_f32_e32 v187, v131, v19
	v_fmac_f32_e32 v224, v128, v8
	v_fmac_f32_e32 v225, v129, v9
	v_fmac_f32_e32 v226, v130, v10
	v_fmac_f32_e32 v227, v131, v11
	v_fmac_f32_e32 v176, v136, v16
	v_fmac_f32_e32 v177, v137, v17
	v_fmac_f32_e32 v178, v138, v18
	v_fmac_f32_e32 v179, v139, v19
	v_fmac_f32_e32 v180, v136, v8
	v_fmac_f32_e32 v181, v137, v9
	v_fmac_f32_e32 v182, v138, v10
	v_fmac_f32_e32 v183, v139, v11
	v_fmac_f32_e32 v184, v136, v0
	v_fmac_f32_e32 v185, v137, v1
	v_fmac_f32_e32 v186, v138, v2
	v_fmac_f32_e32 v187, v139, v3
	v_fmac_f32_e32 v224, v136, v220
	v_fmac_f32_e32 v225, v137, v221
	v_fmac_f32_e32 v226, v138, v222
	v_fmac_f32_e32 v227, v139, v223
	v_add_f32_e32 v176, v140, v176
	v_add_f32_e32 v177, v141, v177
	v_add_f32_e32 v178, v142, v178
	v_add_f32_e32 v179, v143, v179
	v_add_f32_e32 v180, v140, v180
	v_add_f32_e32 v181, v141, v181
	v_add_f32_e32 v182, v142, v182
; __device__ __forceinline__ void st_bf4(bf16_t* p, f32x4 v) { u32x2 w; w.x = pk2(v[0], v[1]); w.y = pk2(v[2], v[3]); *(u32x2*)p = w; }
; __device__ __forceinline__ float sigmoidf_(float x) { return __builtin_amdgcn_rcpf(1.f + __expf(-x)); }
; __device__ __forceinline__ float dpp_ror1(float v) { return __int_as_float(__builtin_amdgcn_update_dpp(0, __float_as_int(v), 0x121, 0xf, 0xf, false)); }
; __device__ __forceinline__ float dpp_rol1(float v) { return __int_as_float(__builtin_amdgcn_update_dpp(0, __float_as_int(v), 0x12F, 0xf, 0xf, false)); }
;     __device__ __forceinline__ void tile(const f32x4 (&acc)[2][2][4][2], const Unit& u, int wr, int wc, int fr, int fq) const {
;     ...
;             const int cv = 128 * u.pn + 32 * wc + 16 * n + 4 * fq, cg = FF + cv;
;             const f32x4 wv0 = *(const f32x4*)(cw + cv), wv1 = *(const f32x4*)(cw + F2 + cv), wv2 = *(const f32x4*)(cw + 2 * F2 + cv), bv = *(const f32x4*)(cb + cv);
;             const f32x4 wg0 = *(const f32x4*)(cw + cg), wg1 = *(const f32x4*)(cw + F2 + cg), wg2 = *(const f32x4*)(cw + 2 * F2 + cg), bg = *(const f32x4*)(cb + cg);
; #pragma unroll
;             for (int ai = 0; ai < 2; ++ai)
; #pragma unroll
;                 for (int m = 0; m < 4; ++m) {
;                     f32x4 r;
; #pragma unroll
;                     for (int i = 0; i < 4; ++i) {
;                         const float xv = acc[ai][0][m][n][i], xg = acc[ai][1][m][n][i];
;                         const float uv = m > 0 ? acc[ai][0][m > 0 ? m - 1 : 0][n][i] : 0.f, ug = m > 0 ? acc[ai][1][m > 0 ? m - 1 : 0][n][i] : 0.f;
;                         const float dv = m < 3 ? acc[ai][0][m < 3 ? m + 1 : 3][n][i] : 0.f, dg = m < 3 ? acc[ai][1][m < 3 ? m + 1 : 3][n][i] : 0.f;
;                         const float pv = dpp_ror1(fr == 15 ? uv : xv), pg = dpp_ror1(fr == 15 ? ug : xg);
;                         const float nv = dpp_rol1(fr == 0 ? dv : xv), ng = dpp_rol1(fr == 0 ? dg : xg);
;                         const float yv = wv0[i] * pv + wv1[i] * xv + wv2[i] * nv + bv[i];
;                         const float yg = wg0[i] * pg + wg1[i] * xg + wg2[i] * ng + bg[i];
;                         r[i] = yg * sigmoidf_(yg) * yv;
;                     }
;                     st_bf4(ACT + (size_t)(u.pm * BM + ai * HALF + wr * 64 + m * 16 + fr) * FF + cv, r);
	v_add_f32_e32 v183, v143, v183
	v_add_f32_e32 v184, v140, v184
	v_add_f32_e32 v185, v141, v185
	v_add_f32_e32 v186, v142, v186
	v_add_f32_e32 v187, v143, v187
	v_add_f32_e32 v224, v140, v224
	v_add_f32_e32 v225, v141, v225
	v_add_f32_e32 v226, v142, v226
	v_add_f32_e32 v227, v143, v227
	v_mov_b32_dpp v216, v4 row_shr:1 row_mask:0xf bank_mask:0xf bound_ctrl:1
	v_mov_b32_dpp v217, v5 row_shr:1 row_mask:0xf bank_mask:0xf bound_ctrl:1
	v_mov_b32_dpp v218, v6 row_shr:1 row_mask:0xf bank_mask:0xf bound_ctrl:1
	v_mov_b32_dpp v219, v7 row_shr:1 row_mask:0xf bank_mask:0xf bound_ctrl:1
	v_mov_b32_dpp v220, v28 row_shl:1 row_mask:0xf bank_mask:0xf bound_ctrl:1
	v_mov_b32_dpp v221, v29 row_shl:1 row_mask:0xf bank_mask:0xf bound_ctrl:1
	v_mov_b32_dpp v222, v30 row_shl:1 row_mask:0xf bank_mask:0xf bound_ctrl:1
	v_mov_b32_dpp v223, v31 row_shl:1 row_mask:0xf bank_mask:0xf bound_ctrl:1
	v_mul_f32_e32 v24, v28, v148
	v_mul_f32_e32 v25, v29, v149
	v_mul_f32_e32 v26, v30, v150
	v_mul_f32_e32 v27, v31, v151
	v_mul_f32_e32 v16, v20, v148
	v_mul_f32_e32 v17, v21, v149
	v_mul_f32_e32 v18, v22, v150
	v_mul_f32_e32 v19, v23, v151
	v_mul_f32_e32 v8, v12, v148
	v_mul_f32_e32 v9, v13, v149
	v_mul_f32_e32 v10, v14, v150
	v_mul_f32_e32 v11, v15, v151
	v_mul_f32_e32 v0, v4, v148
	v_mul_f32_e32 v1, v5, v149
	v_mul_f32_e32 v2, v6, v150
	v_mul_f32_e32 v3, v7, v151
	v_fmac_f32_e32 v24, v144, v216
	v_fmac_f32_e32 v25, v145, v217
	v_fmac_f32_e32 v26, v146, v218
	v_fmac_f32_e32 v27, v147, v219
	v_fmac_f32_e32 v16, v144, v28
	v_fmac_f32_e32 v17, v145, v29
	v_fmac_f32_e32 v18, v146, v30
	v_fmac_f32_e32 v19, v147, v31
	v_fmac_f32_e32 v8, v144, v20
	v_fmac_f32_e32 v9, v145, v21
	v_fmac_f32_e32 v10, v146, v22
	v_fmac_f32_e32 v11, v147, v23
	v_fmac_f32_e32 v0, v144, v12
	v_fmac_f32_e32 v1, v145, v13
	v_fmac_f32_e32 v2, v146, v14
	v_fmac_f32_e32 v3, v147, v15
	v_fmac_f32_e32 v24, v208, v20
	v_fmac_f32_e32 v25, v209, v21
	v_fmac_f32_e32 v26, v210, v22
	v_fmac_f32_e32 v27, v211, v23
	v_fmac_f32_e32 v16, v208, v12
	v_fmac_f32_e32 v17, v209, v13
	v_fmac_f32_e32 v18, v210, v14
	v_fmac_f32_e32 v19, v211, v15
	v_fmac_f32_e32 v8, v208, v4
	v_fmac_f32_e32 v9, v209, v5
	v_fmac_f32_e32 v10, v210, v6
	v_fmac_f32_e32 v11, v211, v7
	v_fmac_f32_e32 v0, v208, v220
	v_fmac_f32_e32 v1, v209, v221
	v_fmac_f32_e32 v2, v210, v222
	v_fmac_f32_e32 v3, v211, v223
	v_add_f32_e32 v24, v212, v24
	v_add_f32_e32 v25, v213, v25
	v_add_f32_e32 v26, v214, v26
	v_add_f32_e32 v27, v215, v27
	v_add_f32_e32 v16, v212, v16
	v_add_f32_e32 v17, v213, v17
	v_add_f32_e32 v18, v214, v18
	v_add_f32_e32 v19, v215, v19
	v_add_f32_e32 v8, v212, v8
	v_add_f32_e32 v9, v213, v9
	v_add_f32_e32 v10, v214, v10
	v_add_f32_e32 v11, v215, v11
	v_add_f32_e32 v0, v212, v0
	v_add_f32_e32 v1, v213, v1
	v_add_f32_e32 v2, v214, v2
	v_add_f32_e32 v3, v215, v3
	v_mul_f32_e32 v28, 0xbfb8aa3b, v176
	v_mul_f32_e32 v29, 0xbfb8aa3b, v177
	v_mul_f32_e32 v30, 0xbfb8aa3b, v178
	v_mul_f32_e32 v31, 0xbfb8aa3b, v179
	v_mul_f32_e32 v20, 0xbfb8aa3b, v180
	v_mul_f32_e32 v21, 0xbfb8aa3b, v181
	v_mul_f32_e32 v22, 0xbfb8aa3b, v182
	v_mul_f32_e32 v23, 0xbfb8aa3b, v183
	v_mul_f32_e32 v12, 0xbfb8aa3b, v184
	v_mul_f32_e32 v13, 0xbfb8aa3b, v185
	v_mul_f32_e32 v14, 0xbfb8aa3b, v186
	v_mul_f32_e32 v15, 0xbfb8aa3b, v187
	v_mul_f32_e32 v4, 0xbfb8aa3b, v224
	v_mul_f32_e32 v5, 0xbfb8aa3b, v225
	v_mul_f32_e32 v6, 0xbfb8aa3b, v226
	v_mul_f32_e32 v7, 0xbfb8aa3b, v227
	v_exp_f32_e32 v28, v28
	v_exp_f32_e32 v29, v29
	v_exp_f32_e32 v30, v30
	v_exp_f32_e32 v31, v31
	v_exp_f32_e32 v20, v20
	v_exp_f32_e32 v21, v21
	v_exp_f32_e32 v22, v22
	v_exp_f32_e32 v23, v23
	v_exp_f32_e32 v12, v12
	v_exp_f32_e32 v13, v13
	v_exp_f32_e32 v14, v14
	v_exp_f32_e32 v15, v15
	v_exp_f32_e32 v4, v4
	v_exp_f32_e32 v5, v5
	v_exp_f32_e32 v6, v6
	v_exp_f32_e32 v7, v7
	v_add_f32_e32 v28, 1.0, v28
	v_add_f32_e32 v29, 1.0, v29
	v_add_f32_e32 v30, 1.0, v30
	v_add_f32_e32 v31, 1.0, v31
	v_add_f32_e32 v20, 1.0, v20
	v_add_f32_e32 v21, 1.0, v21
	v_add_f32_e32 v22, 1.0, v22
	v_add_f32_e32 v23, 1.0, v23
	v_add_f32_e32 v12, 1.0, v12
	v_add_f32_e32 v13, 1.0, v13
	v_add_f32_e32 v14, 1.0, v14
	v_add_f32_e32 v15, 1.0, v15
	v_add_f32_e32 v4, 1.0, v4
	v_add_f32_e32 v5, 1.0, v5
	v_add_f32_e32 v6, 1.0, v6
	v_add_f32_e32 v7, 1.0, v7
	v_rcp_f32_e32 v28, v28
	v_rcp_f32_e32 v29, v29
	v_rcp_f32_e32 v30, v30
	v_rcp_f32_e32 v31, v31
	v_rcp_f32_e32 v20, v20
	v_rcp_f32_e32 v21, v21
	v_rcp_f32_e32 v22, v22
	v_rcp_f32_e32 v23, v23
	v_rcp_f32_e32 v12, v12
	v_rcp_f32_e32 v13, v13
	v_rcp_f32_e32 v14, v14
	v_rcp_f32_e32 v15, v15
	v_rcp_f32_e32 v4, v4
	v_rcp_f32_e32 v5, v5
	v_rcp_f32_e32 v6, v6
	v_rcp_f32_e32 v7, v7
	v_mul_f32_e32 v176, v176, v28
	v_mul_f32_e32 v177, v177, v29
	v_mul_f32_e32 v178, v178, v30
	v_mul_f32_e32 v179, v179, v31
	v_mul_f32_e32 v180, v180, v20
	v_mul_f32_e32 v181, v181, v21
	v_mul_f32_e32 v182, v182, v22
	v_mul_f32_e32 v183, v183, v23
	v_mul_f32_e32 v184, v184, v12
	v_mul_f32_e32 v185, v185, v13
	v_mul_f32_e32 v186, v186, v14
	v_mul_f32_e32 v187, v187, v15
	v_mul_f32_e32 v224, v224, v4
	v_mul_f32_e32 v225, v225, v5
	v_mul_f32_e32 v226, v226, v6
	v_mul_f32_e32 v227, v227, v7
	v_mul_f32_e32 v176, v24, v176
	v_mul_f32_e32 v177, v25, v177
	v_mul_f32_e32 v178, v26, v178
	v_mul_f32_e32 v179, v27, v179
	v_mul_f32_e32 v180, v16, v180
	v_mul_f32_e32 v181, v17, v181
	v_mul_f32_e32 v182, v18, v182
	v_mul_f32_e32 v183, v19, v183
	v_mul_f32_e32 v184, v8, v184
	v_mul_f32_e32 v185, v9, v185
	v_mul_f32_e32 v186, v10, v186
	v_mul_f32_e32 v187, v11, v187
	v_mul_f32_e32 v224, v0, v224
	v_mul_f32_e32 v225, v1, v225
	v_mul_f32_e32 v226, v2, v226
	v_mul_f32_e32 v227, v3, v227
	v_cvt_pk_bf16_f32 v94, v176, v177
	v_cvt_pk_bf16_f32 v95, v178, v179
	v_cvt_pk_bf16_f32 v86, v180, v181
	v_cvt_pk_bf16_f32 v87, v182, v183
	v_cvt_pk_bf16_f32 v78, v184, v185
	v_cvt_pk_bf16_f32 v79, v186, v187
	v_cvt_pk_bf16_f32 v70, v224, v225
	v_cvt_pk_bf16_f32 v71, v226, v227
	s_nop 1
	v_permlane16_swap_b32_e32 v92, v94
	v_permlane16_swap_b32_e32 v93, v95
	v_permlane16_swap_b32_e32 v84, v86
	v_permlane16_swap_b32_e32 v85, v87
	v_permlane16_swap_b32_e32 v76, v78
	v_permlane16_swap_b32_e32 v77, v79
	v_permlane16_swap_b32_e32 v68, v70
	v_permlane16_swap_b32_e32 v69, v71
	global_store_dwordx4 v174, v[92:95], s[0:1]
	v_add_u32_e32 v175, 0x2c00, v174
	global_store_dwordx4 v175, v[84:87], s[0:1]
	v_add_u32_e32 v175, 0x5800, v174
	global_store_dwordx4 v175, v[76:79], s[0:1]
	v_add_u32_e32 v175, 0x8400, v174
	global_store_dwordx4 v175, v[68:71], s[0:1]
	v_lshl_or_b32 v170, s16, 7, v204
	v_lshlrev_b32_e32 v171, 2, v170
	v_add_u32_e32 v172, 0x5800, v171
	global_load_dwordx4 v[230:233], v172, s[56:57]
	global_load_dwordx4 v[234:237], v172, s[12:13]
	global_load_dwordx4 v[238:241], v172, s[14:15]
	global_load_dwordx4 v[242:245], v172, s[58:59]
	global_load_dwordx4 v[246:249], v171, s[56:57]
	global_load_dwordx4 v[250:253], v171, s[12:13]
	s_mov_b32 s98, 1
	s_andn2_b64 vcc, exec, s[20:21]
	s_mov_b64 s[20:21], -1
	s_cbranch_vccnz .LBB0_1795
	s_andn2_b64 vcc, exec, s[2:3]
	s_cbranch_vccnz .LBB0_1794
	s_barrier
	s_branch .LBB0_1794
